# MLP-up epilogue: hoist 8 rowss loads to epilogue top, one wait instead of 8 serialized vmcnt(0)
# speedup vs baseline: 1.0052x; 1.0052x over previous
; __device__ __forceinline__ float ss_rinv(u64 v) { return __builtin_amdgcn_rsqf((float)v * SS_INV + 1e-6f); }
; __device__ __forceinline__ unsigned cvtpk(float lo, float hi) { f32x2 v = {lo, hi}; bf16x2_t b = __builtin_convertvector(v, bf16x2_t); return __builtin_bit_cast(unsigned, b); }
;     __device__ __forceinline__ void operator()(const f32x4 (&acc)[2][2][4][2], const pg8::Unit& u, int wr, int wc, int fr, int fq) const {
;     ...
;                 const int lrow = u.pm * 256 + ai * 128 + wr * 64 + m * 16 + fr, grow = row_base + lrow;
;                 if (grow >= MREAL) continue;
;                 const float ri = ss_rinv(rowss[grow]);
; #pragma unroll
;                 for (int bj = 0; bj < 2; ++bj) {
;                     const int col0 = u.pn * 256 + bj * 128 + wc * 32 + 8 * fq;
;                     f32x4 v0 = acc[ai][bj][m][0] * ri, v1 = acc[ai][bj][m][1] * ri;
;                     if (MODE == 1) {
; #pragma unroll
;                         for (int i = 0; i < 4; ++i) { const float a = fmaxf(v0[i], 0.f), b = fmaxf(v1[i], 0.f); v0[i] = a * a; v1[i] = b * b; }
;                         u32x4 w; w.x = cvtpk(v0[0], v0[1]); w.y = cvtpk(v0[2], v0[3]); w.z = cvtpk(v1[0], v1[1]); w.w = cvtpk(v1[2], v1[3]);
;                         *(u32x4*)(O + (size_t)lrow * DFF + col0) = w;
.LBB0_2035:
	v_lshl_add_u32 v142, s38, 8, v158
	v_lshl_or_b32 v140, s36, 8, v160
	v_add_u32_e32 v144, s66, v142
	v_cmp_gt_i32_e32 vcc, s54, v144
	v_ashrrev_i32_e32 v145, 31, v144
	v_ashrrev_i32_e32 v141, 31, v140
	v_lshl_add_u64 v[186:187], v[144:145], 3, s[12:13]
	global_load_dwordx2 v[170:171], v[186:187], off
	global_load_dwordx2 v[172:173], v[186:187], off offset:128
	global_load_dwordx2 v[174:175], v[186:187], off offset:256
	global_load_dwordx2 v[176:177], v[186:187], off offset:384
	global_load_dwordx2 v[178:179], v[186:187], off offset:1024
	global_load_dwordx2 v[180:181], v[186:187], off offset:1152
	global_load_dwordx2 v[182:183], v[186:187], off offset:1280
	global_load_dwordx2 v[184:185], v[186:187], off offset:1408
	s_waitcnt vmcnt(0)
	s_and_saveexec_b64 s[36:37], vcc
	s_cbranch_execz .LBB0_2037
	v_mov_b64_e32 v[146:147], v[170:171]
	v_ffbh_u32_e32 v143, v147
	v_min_u32_e32 v148, 32, v143
	v_lshlrev_b64 v[146:147], v148, v[146:147]
	v_min_u32_e32 v143, 1, v146
	v_or_b32_e32 v143, v147, v143
	v_cvt_f32_u32_e32 v146, v143
	v_sub_u32_e32 v147, 32, v148
	v_ashrrev_i32_e32 v143, 31, v142
	v_lshlrev_b64 v[148:149], 13, v[142:143]
	v_ldexp_f32 v146, v146, v147
	v_fmamk_f32 v146, v146, 0x30800000, v203
	v_rsq_f32_e32 v146, v146
	v_lshl_add_u64 v[148:149], s[8:9], 0, v[148:149]
	v_lshl_add_u64 v[148:149], v[140:141], 1, v[148:149]
	v_pk_mul_f32 v[128:129], v[128:129], v[146:147] op_sel_hi:[1,0]
	v_pk_mul_f32 v[126:127], v[126:127], v[146:147] op_sel_hi:[1,0]
	v_pk_mul_f32 v[124:125], v[124:125], v[146:147] op_sel_hi:[1,0]
	v_pk_mul_f32 v[122:123], v[122:123], v[146:147] op_sel_hi:[1,0]
	v_pk_mul_f32 v[120:121], v[120:121], v[146:147] op_sel_hi:[1,0]
	v_pk_mul_f32 v[118:119], v[118:119], v[146:147] op_sel_hi:[1,0]
	v_pk_mul_f32 v[116:117], v[116:117], v[146:147] op_sel_hi:[1,0]
	v_pk_mul_f32 v[114:115], v[114:115], v[146:147] op_sel_hi:[1,0]
	v_max_f32_e32 v126, 0, v126
	v_max_f32_e32 v122, 0, v122
	v_max_f32_e32 v127, 0, v127
	v_max_f32_e32 v123, 0, v123
	v_max_f32_e32 v128, 0, v128
	v_max_f32_e32 v124, 0, v124
	v_max_f32_e32 v129, 0, v129
	v_max_f32_e32 v125, 0, v125
	v_max_f32_e32 v118, 0, v118
	v_max_f32_e32 v114, 0, v114
	v_max_f32_e32 v119, 0, v119
	v_max_f32_e32 v115, 0, v115
	v_max_f32_e32 v120, 0, v120
	v_max_f32_e32 v116, 0, v116
	v_max_f32_e32 v121, 0, v121
	v_max_f32_e32 v117, 0, v117
	v_pk_mul_f32 v[126:127], v[126:127], v[126:127]
	v_pk_mul_f32 v[122:123], v[122:123], v[122:123]
	v_pk_mul_f32 v[128:129], v[128:129], v[128:129]
	v_pk_mul_f32 v[124:125], v[124:125], v[124:125]
	v_pk_mul_f32 v[118:119], v[118:119], v[118:119]
	v_pk_mul_f32 v[146:147], v[114:115], v[114:115]
	v_pk_mul_f32 v[120:121], v[120:121], v[120:121]
	v_pk_mul_f32 v[150:151], v[116:117], v[116:117]
	v_cvt_pk_bf16_f32 v114, v126, v127
	v_cvt_pk_bf16_f32 v115, v128, v129
	v_cvt_pk_bf16_f32 v116, v122, v123
	v_cvt_pk_bf16_f32 v117, v124, v125
	v_cvt_pk_bf16_f32 v118, v118, v119
	v_cvt_pk_bf16_f32 v119, v120, v121
	v_cvt_pk_bf16_f32 v120, v146, v147
	v_cvt_pk_bf16_f32 v121, v150, v151
	global_store_dwordx4 v[148:149], v[114:117], off
	global_store_dwordx4 v[148:149], v[118:121], off offset:256
.LBB0_2037:
	s_or_b64 exec, exec, s[36:37]
	v_or_b32_e32 v114, 16, v142
	v_cmp_ge_i32_e32 vcc, s76, v114
	s_and_saveexec_b64 s[36:37], vcc
	s_cbranch_execz .LBB0_2039
	v_mov_b64_e32 v[116:117], v[172:173]
	v_ffbh_u32_e32 v115, v117
	v_min_u32_e32 v118, 32, v115
	v_lshlrev_b64 v[116:117], v118, v[116:117]
	v_min_u32_e32 v115, 1, v116
	v_or_b32_e32 v115, v117, v115
	v_cvt_f32_u32_e32 v116, v115
	v_sub_u32_e32 v117, 32, v118
	v_ashrrev_i32_e32 v115, 31, v114
	v_lshlrev_b64 v[114:115], 13, v[114:115]
	v_ldexp_f32 v116, v116, v117
	v_fmamk_f32 v116, v116, 0x30800000, v203
	v_rsq_f32_e32 v116, v116
	v_lshl_add_u64 v[114:115], s[8:9], 0, v[114:115]
	v_lshl_add_u64 v[114:115], v[140:141], 1, v[114:115]
	v_pk_mul_f32 v[112:113], v[112:113], v[116:117] op_sel_hi:[1,0]
	v_pk_mul_f32 v[110:111], v[110:111], v[116:117] op_sel_hi:[1,0]
	v_pk_mul_f32 v[108:109], v[108:109], v[116:117] op_sel_hi:[1,0]
	v_pk_mul_f32 v[106:107], v[106:107], v[116:117] op_sel_hi:[1,0]
	v_pk_mul_f32 v[104:105], v[104:105], v[116:117] op_sel_hi:[1,0]
	v_pk_mul_f32 v[102:103], v[102:103], v[116:117] op_sel_hi:[1,0]
	v_pk_mul_f32 v[100:101], v[100:101], v[116:117] op_sel_hi:[1,0]
	v_pk_mul_f32 v[98:99], v[98:99], v[116:117] op_sel_hi:[1,0]
	v_max_f32_e32 v110, 0, v110
	v_max_f32_e32 v106, 0, v106
	v_max_f32_e32 v111, 0, v111
	v_max_f32_e32 v107, 0, v107
	v_max_f32_e32 v112, 0, v112
	v_max_f32_e32 v108, 0, v108
	v_max_f32_e32 v113, 0, v113
	v_max_f32_e32 v109, 0, v109
	v_max_f32_e32 v102, 0, v102
	v_max_f32_e32 v98, 0, v98
	v_max_f32_e32 v103, 0, v103
	v_max_f32_e32 v99, 0, v99
	v_max_f32_e32 v104, 0, v104
	v_max_f32_e32 v100, 0, v100
	v_max_f32_e32 v105, 0, v105
	v_max_f32_e32 v101, 0, v101
	v_pk_mul_f32 v[110:111], v[110:111], v[110:111]
	v_pk_mul_f32 v[106:107], v[106:107], v[106:107]
	v_pk_mul_f32 v[112:113], v[112:113], v[112:113]
	v_pk_mul_f32 v[108:109], v[108:109], v[108:109]
	v_pk_mul_f32 v[102:103], v[102:103], v[102:103]
	v_pk_mul_f32 v[116:117], v[98:99], v[98:99]
	v_pk_mul_f32 v[104:105], v[104:105], v[104:105]
	v_pk_mul_f32 v[118:119], v[100:101], v[100:101]
	v_cvt_pk_bf16_f32 v98, v110, v111
	v_cvt_pk_bf16_f32 v99, v112, v113
	v_cvt_pk_bf16_f32 v100, v106, v107
	v_cvt_pk_bf16_f32 v101, v108, v109
	v_cvt_pk_bf16_f32 v102, v102, v103
	v_cvt_pk_bf16_f32 v103, v104, v105
	v_cvt_pk_bf16_f32 v104, v116, v117
	v_cvt_pk_bf16_f32 v105, v118, v119
	global_store_dwordx4 v[114:115], v[98:101], off
	global_store_dwordx4 v[114:115], v[102:105], off offset:256
; __device__ __forceinline__ float ss_rinv(u64 v) { return __builtin_amdgcn_rsqf((float)v * SS_INV + 1e-6f); }
; __device__ __forceinline__ unsigned cvtpk(float lo, float hi) { f32x2 v = {lo, hi}; bf16x2_t b = __builtin_convertvector(v, bf16x2_t); return __builtin_bit_cast(unsigned, b); }
;     __device__ __forceinline__ void operator()(const f32x4 (&acc)[2][2][4][2], const pg8::Unit& u, int wr, int wc, int fr, int fq) const {
;     ...
;                 const int lrow = u.pm * 256 + ai * 128 + wr * 64 + m * 16 + fr, grow = row_base + lrow;
;                 if (grow >= MREAL) continue;
;                 const float ri = ss_rinv(rowss[grow]);
; #pragma unroll
;                 for (int bj = 0; bj < 2; ++bj) {
;                     const int col0 = u.pn * 256 + bj * 128 + wc * 32 + 8 * fq;
;                     f32x4 v0 = acc[ai][bj][m][0] * ri, v1 = acc[ai][bj][m][1] * ri;
;                     if (MODE == 1) {
; #pragma unroll
;                         for (int i = 0; i < 4; ++i) { const float a = fmaxf(v0[i], 0.f), b = fmaxf(v1[i], 0.f); v0[i] = a * a; v1[i] = b * b; }
;                         u32x4 w; w.x = cvtpk(v0[0], v0[1]); w.y = cvtpk(v0[2], v0[3]); w.z = cvtpk(v1[0], v1[1]); w.w = cvtpk(v1[2], v1[3]);
;                         *(u32x4*)(O + (size_t)lrow * DFF + col0) = w;
.LBB0_2039:
	s_or_b64 exec, exec, s[36:37]
	v_or_b32_e32 v98, 32, v142
	v_cmp_ge_i32_e32 vcc, s76, v98
	s_and_saveexec_b64 s[36:37], vcc
	s_cbranch_execz .LBB0_2041
	v_mov_b64_e32 v[100:101], v[174:175]
	v_ffbh_u32_e32 v99, v101
	v_min_u32_e32 v102, 32, v99
	v_lshlrev_b64 v[100:101], v102, v[100:101]
	v_min_u32_e32 v99, 1, v100
	v_or_b32_e32 v99, v101, v99
	v_cvt_f32_u32_e32 v100, v99
	v_sub_u32_e32 v101, 32, v102
	v_ashrrev_i32_e32 v99, 31, v98
	v_lshlrev_b64 v[98:99], 13, v[98:99]
	v_ldexp_f32 v100, v100, v101
	v_fmamk_f32 v100, v100, 0x30800000, v203
	v_rsq_f32_e32 v100, v100
	v_lshl_add_u64 v[98:99], s[8:9], 0, v[98:99]
	v_lshl_add_u64 v[98:99], v[140:141], 1, v[98:99]
	v_pk_mul_f32 v[96:97], v[96:97], v[100:101] op_sel_hi:[1,0]
	v_pk_mul_f32 v[94:95], v[94:95], v[100:101] op_sel_hi:[1,0]
	v_pk_mul_f32 v[92:93], v[92:93], v[100:101] op_sel_hi:[1,0]
	v_pk_mul_f32 v[90:91], v[90:91], v[100:101] op_sel_hi:[1,0]
	v_pk_mul_f32 v[88:89], v[88:89], v[100:101] op_sel_hi:[1,0]
	v_pk_mul_f32 v[86:87], v[86:87], v[100:101] op_sel_hi:[1,0]
	v_pk_mul_f32 v[84:85], v[84:85], v[100:101] op_sel_hi:[1,0]
	v_pk_mul_f32 v[82:83], v[82:83], v[100:101] op_sel_hi:[1,0]
	v_max_f32_e32 v94, 0, v94
	v_max_f32_e32 v90, 0, v90
	v_max_f32_e32 v95, 0, v95
	v_max_f32_e32 v91, 0, v91
	v_max_f32_e32 v96, 0, v96
	v_max_f32_e32 v92, 0, v92
	v_max_f32_e32 v97, 0, v97
	v_max_f32_e32 v93, 0, v93
	v_max_f32_e32 v86, 0, v86
	v_max_f32_e32 v82, 0, v82
	v_max_f32_e32 v87, 0, v87
	v_max_f32_e32 v83, 0, v83
	v_max_f32_e32 v88, 0, v88
	v_max_f32_e32 v84, 0, v84
	v_max_f32_e32 v89, 0, v89
	v_max_f32_e32 v85, 0, v85
	v_pk_mul_f32 v[94:95], v[94:95], v[94:95]
	v_pk_mul_f32 v[90:91], v[90:91], v[90:91]
	v_pk_mul_f32 v[96:97], v[96:97], v[96:97]
	v_pk_mul_f32 v[92:93], v[92:93], v[92:93]
	v_pk_mul_f32 v[86:87], v[86:87], v[86:87]
	v_pk_mul_f32 v[100:101], v[82:83], v[82:83]
	v_pk_mul_f32 v[88:89], v[88:89], v[88:89]
	v_pk_mul_f32 v[102:103], v[84:85], v[84:85]
	v_cvt_pk_bf16_f32 v82, v94, v95
	v_cvt_pk_bf16_f32 v83, v96, v97
	v_cvt_pk_bf16_f32 v84, v90, v91
	v_cvt_pk_bf16_f32 v85, v92, v93
	v_cvt_pk_bf16_f32 v86, v86, v87
	v_cvt_pk_bf16_f32 v87, v88, v89
	v_cvt_pk_bf16_f32 v88, v100, v101
	v_cvt_pk_bf16_f32 v89, v102, v103
	global_store_dwordx4 v[98:99], v[82:85], off
	global_store_dwordx4 v[98:99], v[86:89], off offset:256
.LBB0_2041:
	s_or_b64 exec, exec, s[36:37]
	v_or_b32_e32 v82, 48, v142
	v_cmp_ge_i32_e32 vcc, s76, v82
	s_and_saveexec_b64 s[36:37], vcc
	s_cbranch_execz .LBB0_2043
	v_mov_b64_e32 v[84:85], v[176:177]
	v_ffbh_u32_e32 v83, v85
	v_min_u32_e32 v86, 32, v83
	v_lshlrev_b64 v[84:85], v86, v[84:85]
	v_min_u32_e32 v83, 1, v84
	v_or_b32_e32 v83, v85, v83
	v_cvt_f32_u32_e32 v84, v83
	v_sub_u32_e32 v85, 32, v86
	v_ashrrev_i32_e32 v83, 31, v82
	v_lshlrev_b64 v[82:83], 13, v[82:83]
	v_ldexp_f32 v84, v84, v85
	v_fmamk_f32 v84, v84, 0x30800000, v203
	v_rsq_f32_e32 v84, v84
	v_lshl_add_u64 v[82:83], s[8:9], 0, v[82:83]
	v_lshl_add_u64 v[82:83], v[140:141], 1, v[82:83]
	v_pk_mul_f32 v[80:81], v[80:81], v[84:85] op_sel_hi:[1,0]
	v_pk_mul_f32 v[78:79], v[78:79], v[84:85] op_sel_hi:[1,0]
	v_pk_mul_f32 v[76:77], v[76:77], v[84:85] op_sel_hi:[1,0]
	v_pk_mul_f32 v[74:75], v[74:75], v[84:85] op_sel_hi:[1,0]
	v_pk_mul_f32 v[72:73], v[72:73], v[84:85] op_sel_hi:[1,0]
	v_pk_mul_f32 v[70:71], v[70:71], v[84:85] op_sel_hi:[1,0]
	v_pk_mul_f32 v[68:69], v[68:69], v[84:85] op_sel_hi:[1,0]
	v_pk_mul_f32 v[66:67], v[66:67], v[84:85] op_sel_hi:[1,0]
	v_max_f32_e32 v78, 0, v78
	v_max_f32_e32 v74, 0, v74
	v_max_f32_e32 v79, 0, v79
	v_max_f32_e32 v75, 0, v75
	v_max_f32_e32 v80, 0, v80
	v_max_f32_e32 v76, 0, v76
	v_max_f32_e32 v81, 0, v81
	v_max_f32_e32 v77, 0, v77
	v_max_f32_e32 v70, 0, v70
	v_max_f32_e32 v66, 0, v66
	v_max_f32_e32 v71, 0, v71
	v_max_f32_e32 v67, 0, v67
	v_max_f32_e32 v72, 0, v72
	v_max_f32_e32 v68, 0, v68
	v_max_f32_e32 v73, 0, v73
	v_max_f32_e32 v69, 0, v69
	v_pk_mul_f32 v[78:79], v[78:79], v[78:79]
	v_pk_mul_f32 v[74:75], v[74:75], v[74:75]
	v_pk_mul_f32 v[80:81], v[80:81], v[80:81]
	v_pk_mul_f32 v[76:77], v[76:77], v[76:77]
	v_pk_mul_f32 v[70:71], v[70:71], v[70:71]
	v_pk_mul_f32 v[84:85], v[66:67], v[66:67]
	v_pk_mul_f32 v[72:73], v[72:73], v[72:73]
	v_pk_mul_f32 v[86:87], v[68:69], v[68:69]
	v_cvt_pk_bf16_f32 v66, v78, v79
	v_cvt_pk_bf16_f32 v67, v80, v81
	v_cvt_pk_bf16_f32 v68, v74, v75
	v_cvt_pk_bf16_f32 v69, v76, v77
	v_cvt_pk_bf16_f32 v70, v70, v71
	v_cvt_pk_bf16_f32 v71, v72, v73
	v_cvt_pk_bf16_f32 v72, v84, v85
	v_cvt_pk_bf16_f32 v73, v86, v87
	global_store_dwordx4 v[82:83], v[66:69], off
	global_store_dwordx4 v[82:83], v[70:73], off offset:256
; __device__ __forceinline__ float ss_rinv(u64 v) { return __builtin_amdgcn_rsqf((float)v * SS_INV + 1e-6f); }
; __device__ __forceinline__ unsigned cvtpk(float lo, float hi) { f32x2 v = {lo, hi}; bf16x2_t b = __builtin_convertvector(v, bf16x2_t); return __builtin_bit_cast(unsigned, b); }
;     __device__ __forceinline__ void operator()(const f32x4 (&acc)[2][2][4][2], const pg8::Unit& u, int wr, int wc, int fr, int fq) const {
;     ...
;                 const int lrow = u.pm * 256 + ai * 128 + wr * 64 + m * 16 + fr, grow = row_base + lrow;
;                 if (grow >= MREAL) continue;
;                 const float ri = ss_rinv(rowss[grow]);
; #pragma unroll
;                 for (int bj = 0; bj < 2; ++bj) {
;                     const int col0 = u.pn * 256 + bj * 128 + wc * 32 + 8 * fq;
;                     f32x4 v0 = acc[ai][bj][m][0] * ri, v1 = acc[ai][bj][m][1] * ri;
;                     if (MODE == 1) {
; #pragma unroll
;                         for (int i = 0; i < 4; ++i) { const float a = fmaxf(v0[i], 0.f), b = fmaxf(v1[i], 0.f); v0[i] = a * a; v1[i] = b * b; }
;                         u32x4 w; w.x = cvtpk(v0[0], v0[1]); w.y = cvtpk(v0[2], v0[3]); w.z = cvtpk(v1[0], v1[1]); w.w = cvtpk(v1[2], v1[3]);
;                         *(u32x4*)(O + (size_t)lrow * DFF + col0) = w;
.LBB0_2043:
	s_or_b64 exec, exec, s[36:37]
	v_add_u32_e32 v66, 0x80, v142
	v_add_u32_e32 v68, s66, v66
	v_cmp_gt_i32_e32 vcc, s54, v68
	s_and_saveexec_b64 s[36:37], vcc
	s_cbranch_execz .LBB0_2045
	v_mov_b64_e32 v[68:69], v[178:179]
	v_ffbh_u32_e32 v67, v69
	v_min_u32_e32 v70, 32, v67
	v_lshlrev_b64 v[68:69], v70, v[68:69]
	v_min_u32_e32 v67, 1, v68
	v_or_b32_e32 v67, v69, v67
	v_cvt_f32_u32_e32 v68, v67
	v_sub_u32_e32 v69, 32, v70
	v_ashrrev_i32_e32 v67, 31, v66
	v_lshlrev_b64 v[66:67], 13, v[66:67]
	v_ldexp_f32 v68, v68, v69
	v_fmamk_f32 v68, v68, 0x30800000, v203
	v_rsq_f32_e32 v68, v68
	v_lshl_add_u64 v[66:67], s[8:9], 0, v[66:67]
	v_lshl_add_u64 v[66:67], v[140:141], 1, v[66:67]
	v_pk_mul_f32 v[64:65], v[64:65], v[68:69] op_sel_hi:[1,0]
	v_pk_mul_f32 v[62:63], v[62:63], v[68:69] op_sel_hi:[1,0]
	v_pk_mul_f32 v[60:61], v[60:61], v[68:69] op_sel_hi:[1,0]
	v_pk_mul_f32 v[58:59], v[58:59], v[68:69] op_sel_hi:[1,0]
	v_pk_mul_f32 v[56:57], v[56:57], v[68:69] op_sel_hi:[1,0]
	v_pk_mul_f32 v[54:55], v[54:55], v[68:69] op_sel_hi:[1,0]
	v_pk_mul_f32 v[52:53], v[52:53], v[68:69] op_sel_hi:[1,0]
	v_pk_mul_f32 v[50:51], v[50:51], v[68:69] op_sel_hi:[1,0]
	v_max_f32_e32 v62, 0, v62
	v_max_f32_e32 v58, 0, v58
	v_max_f32_e32 v63, 0, v63
	v_max_f32_e32 v59, 0, v59
	v_max_f32_e32 v64, 0, v64
	v_max_f32_e32 v60, 0, v60
	v_max_f32_e32 v65, 0, v65
	v_max_f32_e32 v61, 0, v61
	v_max_f32_e32 v54, 0, v54
	v_max_f32_e32 v50, 0, v50
	v_max_f32_e32 v55, 0, v55
	v_max_f32_e32 v51, 0, v51
	v_max_f32_e32 v56, 0, v56
	v_max_f32_e32 v52, 0, v52
	v_max_f32_e32 v57, 0, v57
	v_max_f32_e32 v53, 0, v53
	v_pk_mul_f32 v[62:63], v[62:63], v[62:63]
	v_pk_mul_f32 v[58:59], v[58:59], v[58:59]
	v_pk_mul_f32 v[64:65], v[64:65], v[64:65]
	v_pk_mul_f32 v[60:61], v[60:61], v[60:61]
	v_pk_mul_f32 v[54:55], v[54:55], v[54:55]
	v_pk_mul_f32 v[68:69], v[50:51], v[50:51]
	v_pk_mul_f32 v[56:57], v[56:57], v[56:57]
	v_pk_mul_f32 v[70:71], v[52:53], v[52:53]
	v_cvt_pk_bf16_f32 v50, v62, v63
	v_cvt_pk_bf16_f32 v51, v64, v65
	v_cvt_pk_bf16_f32 v52, v58, v59
	v_cvt_pk_bf16_f32 v53, v60, v61
	v_cvt_pk_bf16_f32 v54, v54, v55
	v_cvt_pk_bf16_f32 v55, v56, v57
	v_cvt_pk_bf16_f32 v56, v68, v69
	v_cvt_pk_bf16_f32 v57, v70, v71
	global_store_dwordx4 v[66:67], v[50:53], off
	global_store_dwordx4 v[66:67], v[54:57], off offset:256
.LBB0_2045:
	s_or_b64 exec, exec, s[36:37]
	v_add_u32_e32 v50, 0x90, v142
	v_add_u32_e32 v52, s66, v50
	v_cmp_gt_i32_e32 vcc, s54, v52
	s_and_saveexec_b64 s[36:37], vcc
	s_cbranch_execz .LBB0_2047
	v_mov_b64_e32 v[52:53], v[180:181]
	v_ffbh_u32_e32 v51, v53
	v_min_u32_e32 v54, 32, v51
	v_lshlrev_b64 v[52:53], v54, v[52:53]
	v_min_u32_e32 v51, 1, v52
	v_or_b32_e32 v51, v53, v51
	v_cvt_f32_u32_e32 v52, v51
	v_sub_u32_e32 v53, 32, v54
	v_ashrrev_i32_e32 v51, 31, v50
	v_lshlrev_b64 v[50:51], 13, v[50:51]
	v_ldexp_f32 v52, v52, v53
	v_fmamk_f32 v52, v52, 0x30800000, v203
	v_rsq_f32_e32 v52, v52
	v_lshl_add_u64 v[50:51], s[8:9], 0, v[50:51]
	v_lshl_add_u64 v[50:51], v[140:141], 1, v[50:51]
	v_pk_mul_f32 v[48:49], v[48:49], v[52:53] op_sel_hi:[1,0]
	v_pk_mul_f32 v[46:47], v[46:47], v[52:53] op_sel_hi:[1,0]
	v_pk_mul_f32 v[44:45], v[44:45], v[52:53] op_sel_hi:[1,0]
	v_pk_mul_f32 v[42:43], v[42:43], v[52:53] op_sel_hi:[1,0]
	v_pk_mul_f32 v[40:41], v[40:41], v[52:53] op_sel_hi:[1,0]
	v_pk_mul_f32 v[38:39], v[38:39], v[52:53] op_sel_hi:[1,0]
	v_pk_mul_f32 v[36:37], v[36:37], v[52:53] op_sel_hi:[1,0]
	v_pk_mul_f32 v[34:35], v[34:35], v[52:53] op_sel_hi:[1,0]
	v_max_f32_e32 v46, 0, v46
	v_max_f32_e32 v42, 0, v42
	v_max_f32_e32 v47, 0, v47
	v_max_f32_e32 v43, 0, v43
	v_max_f32_e32 v48, 0, v48
	v_max_f32_e32 v44, 0, v44
	v_max_f32_e32 v49, 0, v49
	v_max_f32_e32 v45, 0, v45
	v_max_f32_e32 v38, 0, v38
	v_max_f32_e32 v34, 0, v34
	v_max_f32_e32 v39, 0, v39
	v_max_f32_e32 v35, 0, v35
	v_max_f32_e32 v40, 0, v40
	v_max_f32_e32 v36, 0, v36
	v_max_f32_e32 v41, 0, v41
	v_max_f32_e32 v37, 0, v37
	v_pk_mul_f32 v[46:47], v[46:47], v[46:47]
	v_pk_mul_f32 v[42:43], v[42:43], v[42:43]
	v_pk_mul_f32 v[48:49], v[48:49], v[48:49]
	v_pk_mul_f32 v[44:45], v[44:45], v[44:45]
	v_pk_mul_f32 v[38:39], v[38:39], v[38:39]
	v_pk_mul_f32 v[52:53], v[34:35], v[34:35]
	v_pk_mul_f32 v[40:41], v[40:41], v[40:41]
	v_pk_mul_f32 v[54:55], v[36:37], v[36:37]
	v_cvt_pk_bf16_f32 v34, v46, v47
	v_cvt_pk_bf16_f32 v35, v48, v49
	v_cvt_pk_bf16_f32 v36, v42, v43
	v_cvt_pk_bf16_f32 v37, v44, v45
	v_cvt_pk_bf16_f32 v38, v38, v39
	v_cvt_pk_bf16_f32 v39, v40, v41
	v_cvt_pk_bf16_f32 v40, v52, v53
	v_cvt_pk_bf16_f32 v41, v54, v55
	global_store_dwordx4 v[50:51], v[34:37], off
	global_store_dwordx4 v[50:51], v[38:41], off offset:256
; __device__ __forceinline__ float ss_rinv(u64 v) { return __builtin_amdgcn_rsqf((float)v * SS_INV + 1e-6f); }
; __device__ __forceinline__ unsigned cvtpk(float lo, float hi) { f32x2 v = {lo, hi}; bf16x2_t b = __builtin_convertvector(v, bf16x2_t); return __builtin_bit_cast(unsigned, b); }
;     __device__ __forceinline__ void operator()(const f32x4 (&acc)[2][2][4][2], const pg8::Unit& u, int wr, int wc, int fr, int fq) const {
;     ...
;                 const int lrow = u.pm * 256 + ai * 128 + wr * 64 + m * 16 + fr, grow = row_base + lrow;
;                 if (grow >= MREAL) continue;
;                 const float ri = ss_rinv(rowss[grow]);
; #pragma unroll
;                 for (int bj = 0; bj < 2; ++bj) {
;                     const int col0 = u.pn * 256 + bj * 128 + wc * 32 + 8 * fq;
;                     f32x4 v0 = acc[ai][bj][m][0] * ri, v1 = acc[ai][bj][m][1] * ri;
;                     if (MODE == 1) {
; #pragma unroll
;                         for (int i = 0; i < 4; ++i) { const float a = fmaxf(v0[i], 0.f), b = fmaxf(v1[i], 0.f); v0[i] = a * a; v1[i] = b * b; }
;                         u32x4 w; w.x = cvtpk(v0[0], v0[1]); w.y = cvtpk(v0[2], v0[3]); w.z = cvtpk(v1[0], v1[1]); w.w = cvtpk(v1[2], v1[3]);
;                         *(u32x4*)(O + (size_t)lrow * DFF + col0) = w;
.LBB0_2047:
	s_or_b64 exec, exec, s[36:37]
	v_add_u32_e32 v34, 0xa0, v142
	v_add_u32_e32 v36, s66, v34
	v_cmp_gt_i32_e32 vcc, s54, v36
	s_and_saveexec_b64 s[36:37], vcc
	s_cbranch_execz .LBB0_2049
	v_mov_b64_e32 v[36:37], v[182:183]
	v_ffbh_u32_e32 v35, v37
	v_min_u32_e32 v38, 32, v35
	v_lshlrev_b64 v[36:37], v38, v[36:37]
	v_min_u32_e32 v35, 1, v36
	v_or_b32_e32 v35, v37, v35
	v_cvt_f32_u32_e32 v36, v35
	v_sub_u32_e32 v37, 32, v38
	v_ashrrev_i32_e32 v35, 31, v34
	v_lshlrev_b64 v[34:35], 13, v[34:35]
	v_ldexp_f32 v36, v36, v37
	v_fmamk_f32 v36, v36, 0x30800000, v203
	v_rsq_f32_e32 v36, v36
	v_lshl_add_u64 v[34:35], s[8:9], 0, v[34:35]
	v_lshl_add_u64 v[34:35], v[140:141], 1, v[34:35]
	v_pk_mul_f32 v[30:31], v[30:31], v[36:37] op_sel_hi:[1,0]
	v_pk_mul_f32 v[28:29], v[28:29], v[36:37] op_sel_hi:[1,0]
	v_pk_mul_f32 v[26:27], v[26:27], v[36:37] op_sel_hi:[1,0]
	v_pk_mul_f32 v[24:25], v[24:25], v[36:37] op_sel_hi:[1,0]
	v_pk_mul_f32 v[22:23], v[22:23], v[36:37] op_sel_hi:[1,0]
	v_pk_mul_f32 v[20:21], v[20:21], v[36:37] op_sel_hi:[1,0]
	v_pk_mul_f32 v[18:19], v[18:19], v[36:37] op_sel_hi:[1,0]
	v_pk_mul_f32 v[16:17], v[16:17], v[36:37] op_sel_hi:[1,0]
	v_max_f32_e32 v28, 0, v28
	v_max_f32_e32 v24, 0, v24
	v_max_f32_e32 v29, 0, v29
	v_max_f32_e32 v25, 0, v25
	v_max_f32_e32 v30, 0, v30
	v_max_f32_e32 v26, 0, v26
	v_max_f32_e32 v31, 0, v31
	v_max_f32_e32 v27, 0, v27
	v_max_f32_e32 v20, 0, v20
	v_max_f32_e32 v16, 0, v16
	v_max_f32_e32 v21, 0, v21
	v_max_f32_e32 v17, 0, v17
	v_max_f32_e32 v22, 0, v22
	v_max_f32_e32 v18, 0, v18
	v_max_f32_e32 v23, 0, v23
	v_max_f32_e32 v19, 0, v19
	v_pk_mul_f32 v[28:29], v[28:29], v[28:29]
	v_pk_mul_f32 v[24:25], v[24:25], v[24:25]
	v_pk_mul_f32 v[30:31], v[30:31], v[30:31]
	v_pk_mul_f32 v[26:27], v[26:27], v[26:27]
	v_pk_mul_f32 v[20:21], v[20:21], v[20:21]
	v_pk_mul_f32 v[36:37], v[16:17], v[16:17]
	v_pk_mul_f32 v[22:23], v[22:23], v[22:23]
	v_pk_mul_f32 v[38:39], v[18:19], v[18:19]
	v_cvt_pk_bf16_f32 v16, v28, v29
	v_cvt_pk_bf16_f32 v17, v30, v31
	v_cvt_pk_bf16_f32 v18, v24, v25
	v_cvt_pk_bf16_f32 v19, v26, v27
	v_cvt_pk_bf16_f32 v20, v20, v21
	v_cvt_pk_bf16_f32 v21, v22, v23
	v_cvt_pk_bf16_f32 v22, v36, v37
	v_cvt_pk_bf16_f32 v23, v38, v39
	global_store_dwordx4 v[34:35], v[16:19], off
	global_store_dwordx4 v[34:35], v[20:23], off offset:256
.LBB0_2049:
	s_or_b64 exec, exec, s[36:37]
	v_add_u32_e32 v16, 0xb0, v142
	v_add_u32_e32 v18, s66, v16
	v_cmp_gt_i32_e32 vcc, s54, v18
	s_and_saveexec_b64 s[36:37], vcc
	s_cbranch_execz .LBB0_2051
	v_mov_b64_e32 v[18:19], v[184:185]
	v_ffbh_u32_e32 v17, v19
	v_min_u32_e32 v20, 32, v17
	v_lshlrev_b64 v[18:19], v20, v[18:19]
	v_min_u32_e32 v17, 1, v18
	v_or_b32_e32 v17, v19, v17
	v_cvt_f32_u32_e32 v18, v17
	v_sub_u32_e32 v19, 32, v20
	v_ashrrev_i32_e32 v17, 31, v16
	v_lshlrev_b64 v[16:17], 13, v[16:17]
	v_ldexp_f32 v18, v18, v19
	v_fmamk_f32 v18, v18, 0x30800000, v203
	v_rsq_f32_e32 v18, v18
	v_lshl_add_u64 v[16:17], s[8:9], 0, v[16:17]
	v_lshl_add_u64 v[16:17], v[140:141], 1, v[16:17]
	v_pk_mul_f32 v[14:15], v[14:15], v[18:19] op_sel_hi:[1,0]
	v_pk_mul_f32 v[12:13], v[12:13], v[18:19] op_sel_hi:[1,0]
	v_pk_mul_f32 v[10:11], v[10:11], v[18:19] op_sel_hi:[1,0]
	v_pk_mul_f32 v[8:9], v[8:9], v[18:19] op_sel_hi:[1,0]
	v_pk_mul_f32 v[6:7], v[6:7], v[18:19] op_sel_hi:[1,0]
	v_pk_mul_f32 v[4:5], v[4:5], v[18:19] op_sel_hi:[1,0]
	v_pk_mul_f32 v[2:3], v[2:3], v[18:19] op_sel_hi:[1,0]
	v_pk_mul_f32 v[0:1], v[0:1], v[18:19] op_sel_hi:[1,0]
	v_max_f32_e32 v12, 0, v12
	v_max_f32_e32 v8, 0, v8
	v_max_f32_e32 v13, 0, v13
	v_max_f32_e32 v9, 0, v9
	v_max_f32_e32 v14, 0, v14
	v_max_f32_e32 v10, 0, v10
	v_max_f32_e32 v15, 0, v15
	v_max_f32_e32 v11, 0, v11
	v_max_f32_e32 v4, 0, v4
	v_max_f32_e32 v0, 0, v0
	v_max_f32_e32 v5, 0, v5
	v_max_f32_e32 v1, 0, v1
	v_max_f32_e32 v6, 0, v6
	v_max_f32_e32 v2, 0, v2
	v_max_f32_e32 v7, 0, v7
	v_max_f32_e32 v3, 0, v3
	v_pk_mul_f32 v[12:13], v[12:13], v[12:13]
	v_pk_mul_f32 v[8:9], v[8:9], v[8:9]
	v_pk_mul_f32 v[14:15], v[14:15], v[14:15]
	v_pk_mul_f32 v[10:11], v[10:11], v[10:11]
	v_pk_mul_f32 v[4:5], v[4:5], v[4:5]
	v_pk_mul_f32 v[18:19], v[0:1], v[0:1]
	v_pk_mul_f32 v[6:7], v[6:7], v[6:7]
	v_pk_mul_f32 v[20:21], v[2:3], v[2:3]
	v_cvt_pk_bf16_f32 v0, v12, v13
	v_cvt_pk_bf16_f32 v1, v14, v15
	v_cvt_pk_bf16_f32 v2, v8, v9
	v_cvt_pk_bf16_f32 v3, v10, v11
	v_cvt_pk_bf16_f32 v4, v4, v5
	v_cvt_pk_bf16_f32 v5, v6, v7
	v_cvt_pk_bf16_f32 v6, v18, v19
	v_cvt_pk_bf16_f32 v7, v20, v21
	global_store_dwordx4 v[16:17], v[0:3], off
	global_store_dwordx4 v[16:17], v[4:7], off offset:256
